# k9 plus nt cache hint on the SwiGLU (P9) epilogue stores
# speedup vs baseline: 1.0005x; 1.0005x over previous
; __device__ __forceinline__ unsigned cvtpk(float lo, float hi) { unsigned r; asm volatile("v_cvt_pk_bf16_f32 %0, %1, %2" : "=v"(r) : "v"(lo), "v"(hi)); return r; }
; __device__ __forceinline__ float sigmoid_f(float x) { return __builtin_amdgcn_rcpf(1.0f + __builtin_amdgcn_exp2f(-x * LOG2E)); }
;     __device__ __forceinline__ void operator()(const f32x4 (&acc)[2][2][4][2], const Unit& u, int wr, int wc, int fr, int fq) const {
;         const int row0 = u.pm * BM + wr * 64 + fr; const int col0 = u.pn * HALF + wc * 32 + 8 * fq;
; #pragma unroll
;         for (int ai = 0; ai < 2; ++ai)
; #pragma unroll
;             for (int m = 0; m < 4; ++m) { bf16* rowp = O + (size_t)(row0 + ai * HALF + m * 16) * DFF + col0;
;                 f32x4 g0 = acc[ai][0][m][0], g1 = acc[ai][0][m][1]; const f32x4 u0 = acc[ai][1][m][0], u1 = acc[ai][1][m][1];
; #pragma unroll
;                 for (int j = 0; j < 4; ++j) { g0[j] = g0[j] * sigmoid_f(g0[j]) * u0[j]; g1[j] = g1[j] * sigmoid_f(g1[j]) * u1[j]; }
;                 u32x4 w; w.x = cvtpk(g0[0], g0[1]); w.y = cvtpk(g0[2], g0[3]); w.z = cvtpk(g1[0], g1[1]); w.w = cvtpk(g1[2], g1[3]);
;                 *(u32x4*)rowp = w; }
;     }
.LBB0_793:
	v_mul_f32_e32 v144, 0xbfb8aa3b, v124
	v_exp_f32_e32 v153, v144
	v_mul_f32_e32 v144, 0xbfb8aa3b, v120
	v_exp_f32_e32 v156, v144
	v_lshl_or_b32 v154, s49, 7, v148
	v_add_f32_e32 v153, 1.0, v153
	v_rcp_f32_e32 v153, v153
	v_add_f32_e32 v156, 1.0, v156
	v_rcp_f32_e32 v158, v156
	v_lshl_add_u32 v152, s18, 8, v146
	v_mul_f32_e32 v124, v124, v153
	v_mul_f32_e32 v116, v124, v116
	v_mul_f32_e32 v124, 0xbfb8aa3b, v125
	v_exp_f32_e32 v124, v124
	v_mul_f32_e32 v153, 0xbfb8aa3b, v121
	v_exp_f32_e32 v153, v153
	v_mul_f32_e32 v120, v120, v158
	v_mul_f32_e32 v120, v120, v112
	v_add_f32_e32 v112, 1.0, v124
	v_rcp_f32_e32 v112, v112
	v_add_f32_e32 v124, 1.0, v153
	v_mul_f32_e32 v153, 0xbfb8aa3b, v126
	v_rcp_f32_e32 v124, v124
	v_exp_f32_e32 v153, v153
	v_mul_f32_e32 v112, v125, v112
	v_mul_f32_e32 v117, v112, v117
	v_mul_f32_e32 v112, v121, v124
	v_add_f32_e32 v121, 1.0, v153
	v_rcp_f32_e32 v121, v121
	v_mul_f32_e32 v124, 0xbfb8aa3b, v122
	v_exp_f32_e32 v124, v124
	v_mul_f32_e32 v125, v112, v113
	v_mul_f32_e32 v112, v126, v121
	v_mul_f32_e32 v113, 0xbfb8aa3b, v127
	v_mul_f32_e32 v121, v112, v118
	v_exp_f32_e32 v113, v113
	v_mul_f32_e32 v118, 0xbfb8aa3b, v123
	v_exp_f32_e32 v118, v118
	v_add_f32_e32 v112, 1.0, v124
	v_rcp_f32_e32 v112, v112
	v_add_f32_e32 v113, 1.0, v113
	v_rcp_f32_e32 v113, v113
	v_add_f32_e32 v118, 1.0, v118
	v_rcp_f32_e32 v118, v118
	v_mul_f32_e32 v112, v122, v112
	v_mul_f32_e32 v122, v112, v114
	v_mul_f32_e32 v112, v127, v113
	v_ashrrev_i32_e32 v155, 31, v154
	v_mov_b64_e32 v[144:145], s[4:5]
	v_mul_f32_e32 v124, v112, v119
	v_mul_f32_e32 v112, v123, v118
	v_mad_i64_i32 v[156:157], s[20:21], v152, s48, v[144:145]
	v_mul_f32_e32 v123, v112, v115
	v_lshlrev_b64 v[112:113], 1, v[154:155]
	v_lshl_add_u64 v[118:119], v[156:157], 0, v[112:113]
	v_cvt_pk_bf16_f32 v114, v116, v117
	v_cvt_pk_bf16_f32 v115, v121, v124
	v_cvt_pk_bf16_f32 v116, v120, v125
	v_cvt_pk_bf16_f32 v117, v122, v123
	global_store_dwordx4 v[118:119], v[114:117], off nt
	s_andn2_b64 vcc, exec, s[0:1]
	s_mov_b64 s[0:1], -1
	v_mul_f32_e32 v114, 0xbfb8aa3b, v108
	v_exp_f32_e32 v114, v114
	v_mul_f32_e32 v115, 0xbfb8aa3b, v104
	v_exp_f32_e32 v115, v115
	v_or_b32_e32 v116, 16, v152
	v_add_f32_e32 v114, 1.0, v114
	v_rcp_f32_e32 v117, v114
	v_add_f32_e32 v114, 1.0, v115
	v_rcp_f32_e32 v118, v114
	v_mad_i64_i32 v[114:115], s[20:21], v116, s48, v[144:145]
	v_mul_f32_e32 v108, v108, v117
	v_mul_f32_e32 v108, v108, v100
	v_mul_f32_e32 v100, v104, v118
	v_mul_f32_e32 v104, 0xbfb8aa3b, v109
	v_exp_f32_e32 v104, v104
	v_mul_f32_e32 v116, 0xbfb8aa3b, v105
	v_mul_f32_e32 v117, v100, v96
	v_exp_f32_e32 v116, v116
	v_add_f32_e32 v96, 1.0, v104
	v_rcp_f32_e32 v96, v96
	v_mul_f32_e32 v104, 0xbfb8aa3b, v110
	v_exp_f32_e32 v104, v104
	v_add_f32_e32 v100, 1.0, v116
	v_mul_f32_e32 v96, v109, v96
	v_rcp_f32_e32 v100, v100
	v_mul_f32_e32 v96, v96, v101
	v_add_f32_e32 v101, 1.0, v104
	v_rcp_f32_e32 v101, v101
	v_mul_f32_e32 v100, v105, v100
	v_mul_f32_e32 v104, 0xbfb8aa3b, v106
	v_mul_f32_e32 v105, v100, v97
	v_mul_f32_e32 v97, v110, v101
	v_exp_f32_e32 v104, v104
	v_mul_f32_e32 v97, v97, v102
	v_mul_f32_e32 v101, 0xbfb8aa3b, v111
	v_mul_f32_e32 v102, 0xbfb8aa3b, v107
	v_exp_f32_e32 v101, v101
	v_exp_f32_e32 v102, v102
	v_add_f32_e32 v100, 1.0, v104
	v_rcp_f32_e32 v100, v100
	v_add_f32_e32 v101, 1.0, v101
	v_add_f32_e32 v102, 1.0, v102
	v_rcp_f32_e32 v101, v101
	v_rcp_f32_e32 v102, v102
	v_mul_f32_e32 v100, v106, v100
	v_mul_f32_e32 v104, v100, v98
	v_mul_f32_e32 v98, v111, v101
	v_mul_f32_e32 v100, v107, v102
	v_mul_f32_e32 v98, v98, v103
	v_mul_f32_e32 v99, v100, v99
	v_lshl_add_u64 v[100:101], v[114:115], 0, v[112:113]
	v_cvt_pk_bf16_f32 v96, v108, v96
	v_cvt_pk_bf16_f32 v97, v97, v98
	v_cvt_pk_bf16_f32 v98, v117, v105
	v_cvt_pk_bf16_f32 v99, v104, v99
	global_store_dwordx4 v[100:101], v[96:99], off nt
	s_nop 1
	v_mul_f32_e32 v96, 0xbfb8aa3b, v92
	v_exp_f32_e32 v96, v96
	v_mul_f32_e32 v97, 0xbfb8aa3b, v88
	v_exp_f32_e32 v97, v97
	v_or_b32_e32 v98, 32, v152
	v_add_f32_e32 v96, 1.0, v96
	v_rcp_f32_e32 v99, v96
	v_add_f32_e32 v96, 1.0, v97
	v_rcp_f32_e32 v100, v96
	v_mad_i64_i32 v[96:97], s[20:21], v98, s48, v[144:145]
	v_mul_f32_e32 v92, v92, v99
	v_mul_f32_e32 v92, v92, v84
	v_mul_f32_e32 v84, v88, v100
	v_mul_f32_e32 v88, 0xbfb8aa3b, v93
	v_exp_f32_e32 v88, v88
	v_mul_f32_e32 v98, 0xbfb8aa3b, v89
	v_mul_f32_e32 v99, v84, v80
	v_exp_f32_e32 v98, v98
	v_add_f32_e32 v80, 1.0, v88
	v_rcp_f32_e32 v80, v80
	v_mul_f32_e32 v88, 0xbfb8aa3b, v94
	v_exp_f32_e32 v88, v88
	v_add_f32_e32 v84, 1.0, v98
	v_mul_f32_e32 v80, v93, v80
	v_rcp_f32_e32 v84, v84
	v_mul_f32_e32 v80, v80, v85
	v_add_f32_e32 v85, 1.0, v88
	v_rcp_f32_e32 v85, v85
	v_mul_f32_e32 v84, v89, v84
	v_mul_f32_e32 v88, 0xbfb8aa3b, v90
	v_mul_f32_e32 v89, v84, v81
	v_mul_f32_e32 v81, v94, v85
	v_exp_f32_e32 v88, v88
	v_mul_f32_e32 v81, v81, v86
	v_mul_f32_e32 v85, 0xbfb8aa3b, v95
	v_mul_f32_e32 v86, 0xbfb8aa3b, v91
	v_exp_f32_e32 v85, v85
	v_exp_f32_e32 v86, v86
	v_add_f32_e32 v84, 1.0, v88
	v_rcp_f32_e32 v84, v84
	v_add_f32_e32 v85, 1.0, v85
	v_add_f32_e32 v86, 1.0, v86
	v_rcp_f32_e32 v85, v85
	v_rcp_f32_e32 v86, v86
	v_mul_f32_e32 v84, v90, v84
	v_mul_f32_e32 v88, v84, v82
	v_mul_f32_e32 v82, v95, v85
	v_mul_f32_e32 v84, v91, v86
	v_mul_f32_e32 v82, v82, v87
	v_mul_f32_e32 v83, v84, v83
	v_lshl_add_u64 v[84:85], v[96:97], 0, v[112:113]
	v_cvt_pk_bf16_f32 v80, v92, v80
	v_cvt_pk_bf16_f32 v81, v81, v82
	v_cvt_pk_bf16_f32 v82, v99, v89
	v_cvt_pk_bf16_f32 v83, v88, v83
	global_store_dwordx4 v[84:85], v[80:83], off nt
	s_nop 1
	v_mul_f32_e32 v80, 0xbfb8aa3b, v76
	v_exp_f32_e32 v80, v80
	v_mul_f32_e32 v81, 0xbfb8aa3b, v72
	v_exp_f32_e32 v81, v81
; __device__ __forceinline__ unsigned cvtpk(float lo, float hi) { unsigned r; asm volatile("v_cvt_pk_bf16_f32 %0, %1, %2" : "=v"(r) : "v"(lo), "v"(hi)); return r; }
; __device__ __forceinline__ float sigmoid_f(float x) { return __builtin_amdgcn_rcpf(1.0f + __builtin_amdgcn_exp2f(-x * LOG2E)); }
;     __device__ __forceinline__ void operator()(const f32x4 (&acc)[2][2][4][2], const Unit& u, int wr, int wc, int fr, int fq) const {
;     ...
;         for (int ai = 0; ai < 2; ++ai)
; #pragma unroll
;             for (int m = 0; m < 4; ++m) { bf16* rowp = O + (size_t)(row0 + ai * HALF + m * 16) * DFF + col0;
;                 f32x4 g0 = acc[ai][0][m][0], g1 = acc[ai][0][m][1]; const f32x4 u0 = acc[ai][1][m][0], u1 = acc[ai][1][m][1];
; #pragma unroll
;                 for (int j = 0; j < 4; ++j) { g0[j] = g0[j] * sigmoid_f(g0[j]) * u0[j]; g1[j] = g1[j] * sigmoid_f(g1[j]) * u1[j]; }
;                 u32x4 w; w.x = cvtpk(g0[0], g0[1]); w.y = cvtpk(g0[2], g0[3]); w.z = cvtpk(g1[0], g1[1]); w.w = cvtpk(g1[2], g1[3]);
;                 *(u32x4*)rowp = w; }
	v_or_b32_e32 v82, 48, v152
	v_add_f32_e32 v80, 1.0, v80
	v_rcp_f32_e32 v83, v80
	v_add_f32_e32 v80, 1.0, v81
	v_rcp_f32_e32 v84, v80
	v_mad_i64_i32 v[80:81], s[20:21], v82, s48, v[144:145]
	v_mul_f32_e32 v76, v76, v83
	v_mul_f32_e32 v76, v76, v68
	v_mul_f32_e32 v68, v72, v84
	v_mul_f32_e32 v72, 0xbfb8aa3b, v77
	v_exp_f32_e32 v72, v72
	v_mul_f32_e32 v82, 0xbfb8aa3b, v73
	v_mul_f32_e32 v83, v68, v64
	v_exp_f32_e32 v82, v82
	v_add_f32_e32 v64, 1.0, v72
	v_rcp_f32_e32 v64, v64
	v_mul_f32_e32 v72, 0xbfb8aa3b, v78
	v_exp_f32_e32 v72, v72
	v_add_f32_e32 v68, 1.0, v82
	v_mul_f32_e32 v64, v77, v64
	v_rcp_f32_e32 v68, v68
	v_mul_f32_e32 v64, v64, v69
	v_add_f32_e32 v69, 1.0, v72
	v_rcp_f32_e32 v69, v69
	v_mul_f32_e32 v68, v73, v68
	v_mul_f32_e32 v72, 0xbfb8aa3b, v74
	v_mul_f32_e32 v73, v68, v65
	v_mul_f32_e32 v65, v78, v69
	v_exp_f32_e32 v72, v72
	v_mul_f32_e32 v65, v65, v70
	v_mul_f32_e32 v69, 0xbfb8aa3b, v79
	v_mul_f32_e32 v70, 0xbfb8aa3b, v75
	v_exp_f32_e32 v69, v69
	v_exp_f32_e32 v70, v70
	v_add_f32_e32 v68, 1.0, v72
	v_rcp_f32_e32 v68, v68
	v_add_f32_e32 v69, 1.0, v69
	v_add_f32_e32 v70, 1.0, v70
	v_rcp_f32_e32 v69, v69
	v_rcp_f32_e32 v70, v70
	v_mul_f32_e32 v68, v74, v68
	v_mul_f32_e32 v72, v68, v66
	v_mul_f32_e32 v66, v79, v69
	v_mul_f32_e32 v68, v75, v70
	v_mul_f32_e32 v66, v66, v71
	v_mul_f32_e32 v67, v68, v67
	v_lshl_add_u64 v[68:69], v[80:81], 0, v[112:113]
	v_cvt_pk_bf16_f32 v64, v76, v64
	v_cvt_pk_bf16_f32 v65, v65, v66
	v_cvt_pk_bf16_f32 v66, v83, v73
	v_cvt_pk_bf16_f32 v67, v72, v67
	global_store_dwordx4 v[68:69], v[64:67], off nt
	s_nop 1
	v_mul_f32_e32 v64, 0xbfb8aa3b, v60
	v_exp_f32_e32 v64, v64
	v_mul_f32_e32 v65, 0xbfb8aa3b, v56
	v_exp_f32_e32 v65, v65
	v_add_u32_e32 v66, 0x80, v152
	v_add_f32_e32 v64, 1.0, v64
	v_rcp_f32_e32 v67, v64
	v_add_f32_e32 v64, 1.0, v65
	v_rcp_f32_e32 v68, v64
	v_mad_i64_i32 v[64:65], s[20:21], v66, s48, v[144:145]
	v_mul_f32_e32 v60, v60, v67
	v_mul_f32_e32 v60, v60, v52
	v_mul_f32_e32 v52, v56, v68
	v_mul_f32_e32 v56, 0xbfb8aa3b, v61
	v_exp_f32_e32 v56, v56
	v_mul_f32_e32 v66, 0xbfb8aa3b, v57
	v_mul_f32_e32 v67, v52, v48
	v_exp_f32_e32 v66, v66
	v_add_f32_e32 v48, 1.0, v56
	v_rcp_f32_e32 v48, v48
	v_mul_f32_e32 v56, 0xbfb8aa3b, v62
	v_exp_f32_e32 v56, v56
	v_add_f32_e32 v52, 1.0, v66
	v_mul_f32_e32 v48, v61, v48
	v_rcp_f32_e32 v52, v52
	v_mul_f32_e32 v48, v48, v53
	v_add_f32_e32 v53, 1.0, v56
	v_rcp_f32_e32 v53, v53
	v_mul_f32_e32 v52, v57, v52
	v_mul_f32_e32 v56, 0xbfb8aa3b, v58
	v_mul_f32_e32 v57, v52, v49
	v_mul_f32_e32 v49, v62, v53
	v_exp_f32_e32 v56, v56
	v_mul_f32_e32 v49, v49, v54
	v_mul_f32_e32 v53, 0xbfb8aa3b, v63
	v_mul_f32_e32 v54, 0xbfb8aa3b, v59
	v_exp_f32_e32 v53, v53
	v_exp_f32_e32 v54, v54
	v_add_f32_e32 v52, 1.0, v56
	v_rcp_f32_e32 v52, v52
	v_add_f32_e32 v53, 1.0, v53
	v_add_f32_e32 v54, 1.0, v54
	v_rcp_f32_e32 v53, v53
	v_rcp_f32_e32 v54, v54
	v_mul_f32_e32 v52, v58, v52
	v_mul_f32_e32 v56, v52, v50
	v_mul_f32_e32 v50, v63, v53
	v_mul_f32_e32 v52, v59, v54
	v_mul_f32_e32 v50, v50, v55
	v_mul_f32_e32 v51, v52, v51
	v_lshl_add_u64 v[52:53], v[64:65], 0, v[112:113]
	v_cvt_pk_bf16_f32 v48, v60, v48
	v_cvt_pk_bf16_f32 v49, v49, v50
	v_cvt_pk_bf16_f32 v50, v67, v57
	v_cvt_pk_bf16_f32 v51, v56, v51
	global_store_dwordx4 v[52:53], v[48:51], off nt
	s_nop 1
	v_mul_f32_e32 v48, 0xbfb8aa3b, v44
	v_exp_f32_e32 v48, v48
	v_mul_f32_e32 v49, 0xbfb8aa3b, v40
	v_exp_f32_e32 v49, v49
	v_add_u32_e32 v50, 0x90, v152
	v_add_f32_e32 v48, 1.0, v48
	v_rcp_f32_e32 v51, v48
	v_add_f32_e32 v48, 1.0, v49
	v_rcp_f32_e32 v52, v48
	v_mad_i64_i32 v[48:49], s[20:21], v50, s48, v[144:145]
	v_mul_f32_e32 v44, v44, v51
	v_mul_f32_e32 v44, v44, v36
	v_mul_f32_e32 v36, v40, v52
	v_mul_f32_e32 v40, 0xbfb8aa3b, v45
	v_exp_f32_e32 v40, v40
	v_mul_f32_e32 v50, 0xbfb8aa3b, v41
	v_mul_f32_e32 v51, v36, v32
	v_exp_f32_e32 v50, v50
	v_add_f32_e32 v32, 1.0, v40
	v_rcp_f32_e32 v32, v32
	v_mul_f32_e32 v40, 0xbfb8aa3b, v46
	v_exp_f32_e32 v40, v40
	v_add_f32_e32 v36, 1.0, v50
	v_mul_f32_e32 v32, v45, v32
	v_rcp_f32_e32 v36, v36
	v_mul_f32_e32 v32, v32, v37
	v_add_f32_e32 v37, 1.0, v40
	v_rcp_f32_e32 v37, v37
	v_mul_f32_e32 v36, v41, v36
	v_mul_f32_e32 v40, 0xbfb8aa3b, v42
	v_mul_f32_e32 v41, v36, v33
; __device__ __forceinline__ unsigned cvtpk(float lo, float hi) { unsigned r; asm volatile("v_cvt_pk_bf16_f32 %0, %1, %2" : "=v"(r) : "v"(lo), "v"(hi)); return r; }
; __device__ __forceinline__ float sigmoid_f(float x) { return __builtin_amdgcn_rcpf(1.0f + __builtin_amdgcn_exp2f(-x * LOG2E)); }
;     __device__ __forceinline__ void operator()(const f32x4 (&acc)[2][2][4][2], const Unit& u, int wr, int wc, int fr, int fq) const {
;     ...
;         for (int ai = 0; ai < 2; ++ai)
; #pragma unroll
;             for (int m = 0; m < 4; ++m) { bf16* rowp = O + (size_t)(row0 + ai * HALF + m * 16) * DFF + col0;
;                 f32x4 g0 = acc[ai][0][m][0], g1 = acc[ai][0][m][1]; const f32x4 u0 = acc[ai][1][m][0], u1 = acc[ai][1][m][1];
; #pragma unroll
;                 for (int j = 0; j < 4; ++j) { g0[j] = g0[j] * sigmoid_f(g0[j]) * u0[j]; g1[j] = g1[j] * sigmoid_f(g1[j]) * u1[j]; }
;                 u32x4 w; w.x = cvtpk(g0[0], g0[1]); w.y = cvtpk(g0[2], g0[3]); w.z = cvtpk(g1[0], g1[1]); w.w = cvtpk(g1[2], g1[3]);
;                 *(u32x4*)rowp = w; }
; template <class Epi, class Sched, bool ALIGN_EPI = false, bool SP2 = false>
; __device__ __forceinline__ void gemm_phase(PG8_LAS unsigned char* lds, const Gemm g, const Sched& S, const Epi& E, const int wv0) {
;     ...
;         if (!has_next) break;
;         if constexpr (!epi_keeps_acc<Epi>::value) {
; #pragma unroll
;         for (int a = 0; a < 2; ++a)
; #pragma unroll
;             for (int b = 0; b < 2; ++b)
; #pragma unroll
;                 for (int m = 0; m < 4; ++m)
; #pragma unroll
;                     for (int n = 0; n < 2; ++n) acc[a][b][m][n] = (f32x4){0.f, 0.f, 0.f, 0.f};
;         }
;         cur = nxt; cA = nA; cB = nB; ++ui;
	v_mul_f32_e32 v33, v46, v37
	v_exp_f32_e32 v40, v40
	v_mul_f32_e32 v33, v33, v38
	v_mul_f32_e32 v37, 0xbfb8aa3b, v47
	v_mul_f32_e32 v38, 0xbfb8aa3b, v43
	v_exp_f32_e32 v37, v37
	v_exp_f32_e32 v38, v38
	v_add_f32_e32 v36, 1.0, v40
	v_rcp_f32_e32 v36, v36
	v_add_f32_e32 v37, 1.0, v37
	v_add_f32_e32 v38, 1.0, v38
	v_rcp_f32_e32 v37, v37
	v_rcp_f32_e32 v38, v38
	v_mul_f32_e32 v36, v42, v36
	v_mul_f32_e32 v40, v36, v34
	v_mul_f32_e32 v34, v47, v37
	v_mul_f32_e32 v36, v43, v38
	v_mul_f32_e32 v34, v34, v39
	v_mul_f32_e32 v35, v36, v35
	v_lshl_add_u64 v[36:37], v[48:49], 0, v[112:113]
	v_cvt_pk_bf16_f32 v32, v44, v32
	v_cvt_pk_bf16_f32 v33, v33, v34
	v_cvt_pk_bf16_f32 v34, v51, v41
	v_cvt_pk_bf16_f32 v35, v40, v35
	global_store_dwordx4 v[36:37], v[32:35], off nt
	s_nop 1
	v_mul_f32_e32 v32, 0xbfb8aa3b, v28
	v_exp_f32_e32 v32, v32
	v_mul_f32_e32 v33, 0xbfb8aa3b, v24
	v_exp_f32_e32 v33, v33
	v_add_u32_e32 v34, 0xa0, v152
	v_add_f32_e32 v32, 1.0, v32
	v_rcp_f32_e32 v35, v32
	v_add_f32_e32 v32, 1.0, v33
	v_rcp_f32_e32 v36, v32
	v_mad_i64_i32 v[32:33], s[20:21], v34, s48, v[144:145]
	v_mul_f32_e32 v28, v28, v35
	v_mul_f32_e32 v28, v28, v20
	v_mul_f32_e32 v20, v24, v36
	v_mul_f32_e32 v24, 0xbfb8aa3b, v29
	v_exp_f32_e32 v24, v24
	v_mul_f32_e32 v34, 0xbfb8aa3b, v25
	v_mul_f32_e32 v35, v20, v16
	v_exp_f32_e32 v34, v34
	v_add_f32_e32 v16, 1.0, v24
	v_rcp_f32_e32 v16, v16
	v_mul_f32_e32 v24, 0xbfb8aa3b, v30
	v_exp_f32_e32 v24, v24
	v_add_f32_e32 v20, 1.0, v34
	v_mul_f32_e32 v16, v29, v16
	v_rcp_f32_e32 v20, v20
	v_mul_f32_e32 v16, v16, v21
	v_add_f32_e32 v21, 1.0, v24
	v_rcp_f32_e32 v21, v21
	v_mul_f32_e32 v20, v25, v20
	v_mul_f32_e32 v24, 0xbfb8aa3b, v26
	v_mul_f32_e32 v25, v20, v17
	v_mul_f32_e32 v17, v30, v21
	v_exp_f32_e32 v24, v24
	v_mul_f32_e32 v17, v17, v22
	v_mul_f32_e32 v21, 0xbfb8aa3b, v31
	v_mul_f32_e32 v22, 0xbfb8aa3b, v27
	v_exp_f32_e32 v21, v21
	v_exp_f32_e32 v22, v22
	v_add_f32_e32 v20, 1.0, v24
	v_rcp_f32_e32 v20, v20
	v_add_f32_e32 v21, 1.0, v21
	v_add_f32_e32 v22, 1.0, v22
	v_rcp_f32_e32 v21, v21
	v_rcp_f32_e32 v22, v22
	v_mul_f32_e32 v20, v26, v20
	v_mul_f32_e32 v24, v20, v18
	v_mul_f32_e32 v18, v31, v21
	v_mul_f32_e32 v20, v27, v22
	v_mul_f32_e32 v18, v18, v23
	v_mul_f32_e32 v19, v20, v19
	v_lshl_add_u64 v[20:21], v[32:33], 0, v[112:113]
	v_cvt_pk_bf16_f32 v16, v28, v16
	v_cvt_pk_bf16_f32 v17, v17, v18
	v_cvt_pk_bf16_f32 v18, v35, v25
	v_cvt_pk_bf16_f32 v19, v24, v19
	global_store_dwordx4 v[20:21], v[16:19], off nt
	s_nop 1
	v_mul_f32_e32 v16, 0xbfb8aa3b, v12
	v_exp_f32_e32 v16, v16
	v_mul_f32_e32 v17, 0xbfb8aa3b, v8
	v_exp_f32_e32 v17, v17
	v_add_u32_e32 v18, 0xb0, v152
	v_add_f32_e32 v16, 1.0, v16
	v_rcp_f32_e32 v19, v16
	v_add_f32_e32 v16, 1.0, v17
	v_rcp_f32_e32 v20, v16
	v_mad_i64_i32 v[16:17], s[20:21], v18, s48, v[144:145]
	v_mul_f32_e32 v12, v12, v19
	v_mul_f32_e32 v12, v12, v4
	v_mul_f32_e32 v4, v8, v20
	v_mul_f32_e32 v8, 0xbfb8aa3b, v13
	v_exp_f32_e32 v8, v8
	v_mul_f32_e32 v18, 0xbfb8aa3b, v9
	v_mul_f32_e32 v19, v4, v0
	v_exp_f32_e32 v18, v18
	v_add_f32_e32 v0, 1.0, v8
	v_rcp_f32_e32 v0, v0
	v_mul_f32_e32 v8, 0xbfb8aa3b, v14
	v_exp_f32_e32 v8, v8
	v_add_f32_e32 v4, 1.0, v18
	v_mul_f32_e32 v0, v13, v0
	v_rcp_f32_e32 v4, v4
	v_mul_f32_e32 v0, v0, v5
	v_add_f32_e32 v5, 1.0, v8
	v_rcp_f32_e32 v5, v5
	v_mul_f32_e32 v4, v9, v4
	v_mul_f32_e32 v8, 0xbfb8aa3b, v10
	v_mul_f32_e32 v9, v4, v1
	v_mul_f32_e32 v1, v14, v5
	v_exp_f32_e32 v8, v8
	v_mul_f32_e32 v1, v1, v6
	v_mul_f32_e32 v5, 0xbfb8aa3b, v15
	v_mul_f32_e32 v6, 0xbfb8aa3b, v11
	v_exp_f32_e32 v5, v5
	v_exp_f32_e32 v6, v6
	v_add_f32_e32 v4, 1.0, v8
	v_rcp_f32_e32 v4, v4
	v_add_f32_e32 v5, 1.0, v5
	v_add_f32_e32 v6, 1.0, v6
	v_rcp_f32_e32 v5, v5
	v_rcp_f32_e32 v6, v6
	v_mul_f32_e32 v4, v10, v4
	v_mul_f32_e32 v8, v4, v2
	v_mul_f32_e32 v2, v15, v5
	v_mul_f32_e32 v4, v11, v6
	v_mul_f32_e32 v2, v2, v7
	v_mul_f32_e32 v3, v4, v3
	v_lshl_add_u64 v[4:5], v[16:17], 0, v[112:113]
	v_cvt_pk_bf16_f32 v0, v12, v0
	v_cvt_pk_bf16_f32 v1, v1, v2
	v_cvt_pk_bf16_f32 v2, v19, v9
	v_cvt_pk_bf16_f32 v3, v8, v3
	global_store_dwordx4 v[4:5], v[0:3], off nt
	s_cbranch_vccnz .LBB0_786
	s_andn2_b64 vcc, exec, s[2:3]
	s_cbranch_vccnz .LBB0_785
	s_barrier
	s_branch .LBB0_785
